# A-fragment reads inside MFMA segment extended to GIN, GOUT and F2 K-loops (7 of 8 fragment groups)
# speedup vs baseline: 1.0105x; 1.0027x over previous
; #define PG8_STAGE(bufoff, gbase, voff) do { _Pragma("unroll") for (int _i = 0; _i < 2; ++_i) \
;         __builtin_amdgcn_global_load_lds((const unsigned*)((const char*)(gbase) + (voff)[_i]), (PG8_LAS unsigned*)(lds + (bufoff) + ldsw + _i * 8192), 16, 0, 0); } while (0)
; #define PG8_LDA(dst, b, h) do { _Pragma("unroll") for (int m = 0; m < 4; ++m) _Pragma("unroll") for (int k = 0; k < 2; ++k) dst[m][k] = *(const PG8_LAS bf16x8*)(lds + PG8_SA(b, h) + aoff + m * 2048 + k * 1024); } while (0)
; #define PG8_LDB(dst, b, h) do { _Pragma("unroll") for (int n = 0; n < 2; ++n) _Pragma("unroll") for (int k = 0; k < 2; ++k) dst[n][k] = *(const PG8_LAS bf16x8*)(lds + PG8_SB(b, h) + boff + n * 2048 + k * 1024); } while (0)
; #define PG8_MMA(ai, bj, At, Bt) do { __builtin_amdgcn_s_setprio(1); _Pragma("unroll") for (int m = 0; m < 4; ++m) _Pragma("unroll") for (int n = 0; n < 2; ++n) _Pragma("unroll") for (int k = 0; k < 2; ++k) \
;         acc[ai][bj][m][n] = __builtin_amdgcn_mfma_f32_16x16x32_bf16(Bt[n][k], At[m][k], acc[ai][bj][m][n], 0, 0, 0); __builtin_amdgcn_s_setprio(0); } while (0)
; #define PG8_WAIT_V(n) asm volatile("s_waitcnt vmcnt(" #n ")" ::: "memory")
; #define PG8_WAIT_L(n) asm volatile("s_waitcnt lgkmcnt(" #n ")" ::: "memory")
; template <class Epi, class Sched, bool ALIGN_EPI = true, bool SP2 = true>
; __device__ __forceinline__ void gemm_phase(PG8_LAS unsigned char* lds, const Gemm g, const Sched& S, const Epi& E, const int tid) {
;     ...
;             const bool last = (t == nt - 2);
;             const char* a1 = cA + (size_t)(t + 1) * kstep;
;             const char* a2 = last ? nA : cA + (size_t)(t + 2) * kstep; const char* b2 = last ? nB : cB + (size_t)(t + 2) * kstep;
;             const char* a3 = a2 + kstep; const char* b3 = b2 + kstep;
;             if (last && has_next) S.a_ready(nxt);
;             if constexpr (SP2) {
;             PG8_LDB(B0, 0, 0); PG8_LDB(B1, 0, 1); PG8_SCHED; PG8_LDA(At, 0, 0); PG8_STAGE(PG8_SA(1, 1), a1 + hstepA, voffA);
;             PG8_WAIT_V(8); PG8_WAIT_L(0); PG8_BAR; PG8_MMA(0, 0, At, B0); PG8_MMA(0, 1, At, B1); PG8_BAR; PG8_SCHED;
;             PG8_LDA(At, 0, 1); PG8_STAGE(PG8_SB(0, 0), b2, voffB); PG8_STAGE(PG8_SB(0, 1), b2 + hstepB, voffB); PG8_STAGE(PG8_SA(0, 0), a2, voffA);
;             PG8_WAIT_V(8); PG8_WAIT_L(0); PG8_BAR; PG8_MMA(1, 0, At, B0); PG8_MMA(1, 1, At, B1); PG8_BAR; PG8_SCHED;
.LBB0_381:
	s_add_u32 s25, s62, 0xfff80080
	s_addc_u32 s26, s63, -1
	s_add_i32 s27, 0, 0x10000
	s_cmp_eq_u32 s24, 28
	s_cselect_b32 s69, s18, s26
	s_cselect_b32 s68, s19, s25
	s_cselect_b32 s67, s20, s23
	s_cselect_b32 s66, s21, s22
	s_add_i32 s25, 0, 0x14000
	v_add_u32_e32 v158, s27, v163
	v_add_u32_e32 v165, s25, v163
	ds_read_b128 v[146:149], v158
	ds_read_b128 v[150:153], v158 offset:1024
	ds_read_b128 v[154:157], v158 offset:2048
	ds_read_b128 v[158:161], v158 offset:3072
	ds_read_b128 v[166:169], v165
	ds_read_b128 v[170:173], v165 offset:1024
	ds_read_b128 v[174:177], v165 offset:2048
	ds_read_b128 v[178:181], v165 offset:3072
	s_add_i32 m0, s82, 0xc000
	ds_read_b128 v[182:185], v164
	ds_read_b128 v[186:189], v164 offset:1024
	ds_read_b128 v[190:193], v164 offset:2048
	ds_read_b128 v[194:197], v164 offset:3072
	ds_read_b128 v[206:209], v164 offset:4096
	ds_read_b128 v[210:213], v164 offset:5120
	ds_read_b128 v[222:225], v164 offset:6144
	ds_read_b128 v[226:229], v164 offset:7168
	global_load_lds_dwordx4 v142, s[62:63]
	s_add_i32 m0, s82, 0xe000
	s_nop 0
	global_load_lds_dwordx4 v144, s[62:63]
	s_waitcnt vmcnt(8)
	s_waitcnt lgkmcnt(0)
	s_barrier
	s_setprio 1
	s_waitcnt lgkmcnt(0)
	v_mfma_f32_16x16x32_bf16 v[126:129], v[146:149], v[182:185], v[126:129]
	v_mfma_f32_16x16x32_bf16 v[122:125], v[154:157], v[182:185], v[122:125]
	ds_read_b128 v[200:203], v164 offset:16384
	v_mfma_f32_16x16x32_bf16 v[110:113], v[146:149], v[190:193], v[110:113]
	v_mfma_f32_16x16x32_bf16 v[106:109], v[154:157], v[190:193], v[106:109]
	v_mfma_f32_16x16x32_bf16 v[92:95], v[146:149], v[206:209], v[92:95]
	v_mfma_f32_16x16x32_bf16 v[88:91], v[154:157], v[206:209], v[88:91]
	ds_read_b128 v[218:221], v164 offset:17408
	v_mfma_f32_16x16x32_bf16 v[76:79], v[146:149], v[222:225], v[76:79]
	v_mfma_f32_16x16x32_bf16 v[72:75], v[154:157], v[222:225], v[72:75]
	v_mfma_f32_16x16x32_bf16 v[126:129], v[150:153], v[186:189], v[126:129]
	v_mfma_f32_16x16x32_bf16 v[122:125], v[158:161], v[186:189], v[122:125]
	ds_read_b128 v[230:233], v164 offset:18432
	v_mfma_f32_16x16x32_bf16 v[110:113], v[150:153], v[194:197], v[110:113]
	v_mfma_f32_16x16x32_bf16 v[106:109], v[158:161], v[194:197], v[106:109]
	v_mfma_f32_16x16x32_bf16 v[92:95], v[150:153], v[210:213], v[92:95]
	v_mfma_f32_16x16x32_bf16 v[88:91], v[158:161], v[210:213], v[88:91]
	ds_read_b128 v[234:237], v164 offset:19456
	v_mfma_f32_16x16x32_bf16 v[76:79], v[150:153], v[226:229], v[76:79]
	v_mfma_f32_16x16x32_bf16 v[72:75], v[158:161], v[226:229], v[72:75]
	s_setprio 0
	s_setprio 1
	v_mfma_f32_16x16x32_bf16 v[118:121], v[166:169], v[182:185], v[118:121]
	v_mfma_f32_16x16x32_bf16 v[114:117], v[174:177], v[182:185], v[114:117]
	ds_read_b128 v[238:241], v164 offset:20480
	v_mfma_f32_16x16x32_bf16 v[102:105], v[166:169], v[190:193], v[102:105]
	v_mfma_f32_16x16x32_bf16 v[98:101], v[174:177], v[190:193], v[98:101]
	v_mfma_f32_16x16x32_bf16 v[84:87], v[166:169], v[206:209], v[84:87]
	v_mfma_f32_16x16x32_bf16 v[80:83], v[174:177], v[206:209], v[80:83]
	ds_read_b128 v[242:245], v164 offset:21504
	v_mfma_f32_16x16x32_bf16 v[68:71], v[166:169], v[222:225], v[68:71]
	v_mfma_f32_16x16x32_bf16 v[64:67], v[174:177], v[222:225], v[64:67]
	v_mfma_f32_16x16x32_bf16 v[118:121], v[170:173], v[186:189], v[118:121]
	v_mfma_f32_16x16x32_bf16 v[114:117], v[178:181], v[186:189], v[114:117]
	ds_read_b128 v[246:249], v164 offset:22528
	v_mfma_f32_16x16x32_bf16 v[102:105], v[170:173], v[194:197], v[102:105]
	v_mfma_f32_16x16x32_bf16 v[98:101], v[178:181], v[194:197], v[98:101]
	v_mfma_f32_16x16x32_bf16 v[84:87], v[170:173], v[210:213], v[84:87]
	v_mfma_f32_16x16x32_bf16 v[80:83], v[178:181], v[210:213], v[80:83]
	v_mfma_f32_16x16x32_bf16 v[68:71], v[170:173], v[226:229], v[68:71]
	v_mfma_f32_16x16x32_bf16 v[64:67], v[178:181], v[226:229], v[64:67]
	s_setprio 0
	s_barrier
	s_add_i32 s26, s27, s73
	s_mov_b32 m0, s26
	ds_read_b128 v[226:229], v164 offset:23552
	global_load_lds_dwordx4 v132, s[66:67]
	s_add_i32 m0, s26, 0x2000
	s_add_u32 s26, s66, 0x80000
	s_addc_u32 s27, s67, 0
	s_add_i32 s25, s25, s73
	global_load_lds_dwordx4 v136, s[66:67]
	s_mov_b32 m0, s25
	s_nop 0
	global_load_lds_dwordx4 v132, s[26:27]
	s_add_i32 m0, s25, 0x2000
	s_nop 0
	global_load_lds_dwordx4 v136, s[26:27]
	s_mov_b32 m0, s82
	s_nop 0
	global_load_lds_dwordx4 v130, s[68:69]
	s_mov_b32 m0, s83
	s_nop 0
	global_load_lds_dwordx4 v134, s[68:69]
	s_waitcnt vmcnt(6)
	s_waitcnt lgkmcnt(0)
	s_barrier
	s_setprio 1
	s_waitcnt lgkmcnt(0)
	v_mfma_f32_16x16x32_bf16 v[60:63], v[146:149], v[200:203], v[60:63]
	v_mfma_f32_16x16x32_bf16 v[56:59], v[154:157], v[200:203], v[56:59]
	v_mfma_f32_16x16x32_bf16 v[44:47], v[146:149], v[230:233], v[44:47]
	v_mfma_f32_16x16x32_bf16 v[40:43], v[154:157], v[230:233], v[40:43]
	v_mfma_f32_16x16x32_bf16 v[28:31], v[146:149], v[238:241], v[28:31]
	v_mfma_f32_16x16x32_bf16 v[24:27], v[154:157], v[238:241], v[24:27]
	v_mfma_f32_16x16x32_bf16 v[12:15], v[146:149], v[246:249], v[12:15]
	v_mfma_f32_16x16x32_bf16 v[8:11], v[154:157], v[246:249], v[8:11]
	v_mfma_f32_16x16x32_bf16 v[60:63], v[150:153], v[218:221], v[60:63]
	v_mfma_f32_16x16x32_bf16 v[56:59], v[158:161], v[218:221], v[56:59]
	v_mfma_f32_16x16x32_bf16 v[44:47], v[150:153], v[234:237], v[44:47]
	v_mfma_f32_16x16x32_bf16 v[40:43], v[158:161], v[234:237], v[40:43]
	v_mfma_f32_16x16x32_bf16 v[28:31], v[150:153], v[242:245], v[28:31]
	v_mfma_f32_16x16x32_bf16 v[24:27], v[158:161], v[242:245], v[24:27]
	v_mfma_f32_16x16x32_bf16 v[12:15], v[150:153], v[226:229], v[12:15]
	v_mfma_f32_16x16x32_bf16 v[8:11], v[158:161], v[226:229], v[8:11]
	s_setprio 0
	s_setprio 1
	v_mfma_f32_16x16x32_bf16 v[52:55], v[166:169], v[200:203], v[52:55]
	v_mfma_f32_16x16x32_bf16 v[48:51], v[174:177], v[200:203], v[48:51]
	v_mfma_f32_16x16x32_bf16 v[36:39], v[166:169], v[230:233], v[36:39]
	v_mfma_f32_16x16x32_bf16 v[32:35], v[174:177], v[230:233], v[32:35]
	v_mfma_f32_16x16x32_bf16 v[20:23], v[166:169], v[238:241], v[20:23]
	v_mfma_f32_16x16x32_bf16 v[16:19], v[174:177], v[238:241], v[16:19]
	v_mfma_f32_16x16x32_bf16 v[4:7], v[166:169], v[246:249], v[4:7]
	v_mfma_f32_16x16x32_bf16 v[0:3], v[174:177], v[246:249], v[0:3]
	v_mfma_f32_16x16x32_bf16 v[52:55], v[170:173], v[218:221], v[52:55]
	v_mfma_f32_16x16x32_bf16 v[48:51], v[178:181], v[218:221], v[48:51]
	v_mfma_f32_16x16x32_bf16 v[36:39], v[170:173], v[234:237], v[36:39]
	v_mfma_f32_16x16x32_bf16 v[32:35], v[178:181], v[234:237], v[32:35]
	v_mfma_f32_16x16x32_bf16 v[20:23], v[170:173], v[242:245], v[20:23]
	v_mfma_f32_16x16x32_bf16 v[16:19], v[178:181], v[242:245], v[16:19]
	v_mfma_f32_16x16x32_bf16 v[4:7], v[170:173], v[226:229], v[4:7]
	v_mfma_f32_16x16x32_bf16 v[0:3], v[178:181], v[226:229], v[0:3]
	s_setprio 0
	s_barrier
; #define PG8_STAGE(bufoff, gbase, voff) do { _Pragma("unroll") for (int _i = 0; _i < 2; ++_i) \
;         __builtin_amdgcn_global_load_lds((const unsigned*)((const char*)(gbase) + (voff)[_i]), (PG8_LAS unsigned*)(lds + (bufoff) + ldsw + _i * 8192), 16, 0, 0); } while (0)
; #define PG8_LDA(dst, b, h) do { _Pragma("unroll") for (int m = 0; m < 4; ++m) _Pragma("unroll") for (int k = 0; k < 2; ++k) dst[m][k] = *(const PG8_LAS bf16x8*)(lds + PG8_SA(b, h) + aoff + m * 2048 + k * 1024); } while (0)
; #define PG8_LDB(dst, b, h) do { _Pragma("unroll") for (int n = 0; n < 2; ++n) _Pragma("unroll") for (int k = 0; k < 2; ++k) dst[n][k] = *(const PG8_LAS bf16x8*)(lds + PG8_SB(b, h) + boff + n * 2048 + k * 1024); } while (0)
; #define PG8_MMA(ai, bj, At, Bt) do { __builtin_amdgcn_s_setprio(1); _Pragma("unroll") for (int m = 0; m < 4; ++m) _Pragma("unroll") for (int n = 0; n < 2; ++n) _Pragma("unroll") for (int k = 0; k < 2; ++k) \
;         acc[ai][bj][m][n] = __builtin_amdgcn_mfma_f32_16x16x32_bf16(Bt[n][k], At[m][k], acc[ai][bj][m][n], 0, 0, 0); __builtin_amdgcn_s_setprio(0); } while (0)
; #define PG8_WAIT_V(n) asm volatile("s_waitcnt vmcnt(" #n ")" ::: "memory")
; #define PG8_WAIT_L(n) asm volatile("s_waitcnt lgkmcnt(" #n ")" ::: "memory")
; #define PG8_BAR __builtin_amdgcn_s_barrier()
; #define PG8_SCHED __builtin_amdgcn_sched_barrier(0)
; template <class Epi, class Sched, bool ALIGN_EPI = true, bool SP2 = true>
; __device__ __forceinline__ void gemm_phase(PG8_LAS unsigned char* lds, const Gemm g, const Sched& S, const Epi& E, const int tid) {
;     ...
;             PG8_LDB(B0, 1, 0); PG8_LDB(B1, 1, 1); PG8_SCHED; PG8_LDA(At, 1, 0); PG8_STAGE(PG8_SA(0, 1), a2 + hstepA, voffA);
;             PG8_WAIT_V(8); PG8_WAIT_L(0); PG8_BAR; PG8_MMA(0, 0, At, B0); PG8_MMA(0, 1, At, B1); PG8_BAR; PG8_SCHED;
;             PG8_LDA(At, 1, 1); PG8_STAGE(PG8_SB(1, 0), b3, voffB); PG8_STAGE(PG8_SB(1, 1), b3 + hstepB, voffB); PG8_STAGE(PG8_SA(1, 0), a3, voffA);
;             PG8_WAIT_V(8); PG8_WAIT_L(0); PG8_BAR; PG8_MMA(1, 0, At, B0); PG8_MMA(1, 1, At, B1); PG8_BAR; PG8_SCHED;
	s_add_i32 s25, 0, 0x18000
	s_add_i32 s28, 0, 0x1c000
	v_add_u32_e32 v158, s25, v163
	v_add_u32_e32 v165, s28, v163
	ds_read_b128 v[146:149], v158
	ds_read_b128 v[150:153], v158 offset:1024
	ds_read_b128 v[154:157], v158 offset:2048
	ds_read_b128 v[158:161], v158 offset:3072
	ds_read_b128 v[166:169], v165
	ds_read_b128 v[170:173], v165 offset:1024
	ds_read_b128 v[174:177], v165 offset:2048
	ds_read_b128 v[178:181], v165 offset:3072
	s_add_u32 s26, s68, 0x80000
	s_addc_u32 s27, s69, 0
	s_mov_b32 m0, s84
	ds_read_b128 v[182:185], v164 offset:32768
	ds_read_b128 v[186:189], v164 offset:33792
	ds_read_b128 v[190:193], v164 offset:34816
	ds_read_b128 v[194:197], v164 offset:35840
	ds_read_b128 v[206:209], v164 offset:36864
	ds_read_b128 v[210:213], v164 offset:37888
	ds_read_b128 v[222:225], v164 offset:38912
	ds_read_b128 v[226:229], v164 offset:39936
	global_load_lds_dwordx4 v130, s[26:27]
	s_mov_b32 m0, s85
	s_nop 0
	global_load_lds_dwordx4 v134, s[26:27]
	s_waitcnt vmcnt(8)
	s_waitcnt lgkmcnt(0)
	s_barrier
	s_setprio 1
	s_waitcnt lgkmcnt(0)
	v_mfma_f32_16x16x32_bf16 v[126:129], v[146:149], v[182:185], v[126:129]
	v_mfma_f32_16x16x32_bf16 v[122:125], v[154:157], v[182:185], v[122:125]
	ds_read_b128 v[200:203], v164 offset:49152
	v_mfma_f32_16x16x32_bf16 v[110:113], v[146:149], v[190:193], v[110:113]
	v_mfma_f32_16x16x32_bf16 v[106:109], v[154:157], v[190:193], v[106:109]
	v_mfma_f32_16x16x32_bf16 v[92:95], v[146:149], v[206:209], v[92:95]
	v_mfma_f32_16x16x32_bf16 v[88:91], v[154:157], v[206:209], v[88:91]
	ds_read_b128 v[218:221], v164 offset:50176
	v_mfma_f32_16x16x32_bf16 v[76:79], v[146:149], v[222:225], v[76:79]
	v_mfma_f32_16x16x32_bf16 v[72:75], v[154:157], v[222:225], v[72:75]
	v_mfma_f32_16x16x32_bf16 v[126:129], v[150:153], v[186:189], v[126:129]
	v_mfma_f32_16x16x32_bf16 v[122:125], v[158:161], v[186:189], v[122:125]
	ds_read_b128 v[230:233], v164 offset:51200
	v_mfma_f32_16x16x32_bf16 v[110:113], v[150:153], v[194:197], v[110:113]
	v_mfma_f32_16x16x32_bf16 v[106:109], v[158:161], v[194:197], v[106:109]
	v_mfma_f32_16x16x32_bf16 v[92:95], v[150:153], v[210:213], v[92:95]
	v_mfma_f32_16x16x32_bf16 v[88:91], v[158:161], v[210:213], v[88:91]
	ds_read_b128 v[234:237], v164 offset:52224
	v_mfma_f32_16x16x32_bf16 v[76:79], v[150:153], v[226:229], v[76:79]
	v_mfma_f32_16x16x32_bf16 v[72:75], v[158:161], v[226:229], v[72:75]
	s_setprio 0
	s_setprio 1
	v_mfma_f32_16x16x32_bf16 v[118:121], v[166:169], v[182:185], v[118:121]
	v_mfma_f32_16x16x32_bf16 v[114:117], v[174:177], v[182:185], v[114:117]
	ds_read_b128 v[238:241], v164 offset:53248
	v_mfma_f32_16x16x32_bf16 v[102:105], v[166:169], v[190:193], v[102:105]
	v_mfma_f32_16x16x32_bf16 v[98:101], v[174:177], v[190:193], v[98:101]
	v_mfma_f32_16x16x32_bf16 v[84:87], v[166:169], v[206:209], v[84:87]
	v_mfma_f32_16x16x32_bf16 v[80:83], v[174:177], v[206:209], v[80:83]
	ds_read_b128 v[242:245], v164 offset:54272
	v_mfma_f32_16x16x32_bf16 v[68:71], v[166:169], v[222:225], v[68:71]
	v_mfma_f32_16x16x32_bf16 v[64:67], v[174:177], v[222:225], v[64:67]
	v_mfma_f32_16x16x32_bf16 v[118:121], v[170:173], v[186:189], v[118:121]
	v_mfma_f32_16x16x32_bf16 v[114:117], v[178:181], v[186:189], v[114:117]
	ds_read_b128 v[246:249], v164 offset:55296
	v_mfma_f32_16x16x32_bf16 v[102:105], v[170:173], v[194:197], v[102:105]
	v_mfma_f32_16x16x32_bf16 v[98:101], v[178:181], v[194:197], v[98:101]
	v_mfma_f32_16x16x32_bf16 v[84:87], v[170:173], v[210:213], v[84:87]
	v_mfma_f32_16x16x32_bf16 v[80:83], v[178:181], v[210:213], v[80:83]
	v_mfma_f32_16x16x32_bf16 v[68:71], v[170:173], v[226:229], v[68:71]
	v_mfma_f32_16x16x32_bf16 v[64:67], v[178:181], v[226:229], v[64:67]
	s_setprio 0
	s_barrier
	s_add_i32 s25, s25, s73
	s_add_u32 s4, s66, 0x80
	s_addc_u32 s5, s67, 0
	s_mov_b32 m0, s25
	ds_read_b128 v[226:229], v164 offset:56320
	global_load_lds_dwordx4 v132, s[4:5]
	s_add_i32 m0, s25, 0x2000
	s_add_u32 s26, s66, 0x80080
	s_addc_u32 s27, s67, 0
	s_add_i32 s25, s28, s73
	global_load_lds_dwordx4 v136, s[4:5]
	s_mov_b32 m0, s25
	s_nop 0
	global_load_lds_dwordx4 v132, s[26:27]
	s_add_i32 m0, s25, 0x2000
	s_nop 0
	global_load_lds_dwordx4 v136, s[26:27]
	s_add_u32 s4, s68, 0x80
	s_addc_u32 s5, s69, 0
	s_mov_b32 m0, s88
	s_nop 0
	global_load_lds_dwordx4 v130, s[4:5]
	s_mov_b32 m0, s89
	s_nop 0
	global_load_lds_dwordx4 v134, s[4:5]
	s_waitcnt vmcnt(6)
	s_waitcnt lgkmcnt(0)
	s_barrier
	s_setprio 1
	s_waitcnt lgkmcnt(0)
	v_mfma_f32_16x16x32_bf16 v[60:63], v[146:149], v[200:203], v[60:63]
	v_mfma_f32_16x16x32_bf16 v[56:59], v[154:157], v[200:203], v[56:59]
	v_mfma_f32_16x16x32_bf16 v[44:47], v[146:149], v[230:233], v[44:47]
	v_mfma_f32_16x16x32_bf16 v[40:43], v[154:157], v[230:233], v[40:43]
	v_mfma_f32_16x16x32_bf16 v[28:31], v[146:149], v[238:241], v[28:31]
	v_mfma_f32_16x16x32_bf16 v[24:27], v[154:157], v[238:241], v[24:27]
	v_mfma_f32_16x16x32_bf16 v[12:15], v[146:149], v[246:249], v[12:15]
	v_mfma_f32_16x16x32_bf16 v[8:11], v[154:157], v[246:249], v[8:11]
	v_mfma_f32_16x16x32_bf16 v[60:63], v[150:153], v[218:221], v[60:63]
	v_mfma_f32_16x16x32_bf16 v[56:59], v[158:161], v[218:221], v[56:59]
	v_mfma_f32_16x16x32_bf16 v[44:47], v[150:153], v[234:237], v[44:47]
	v_mfma_f32_16x16x32_bf16 v[40:43], v[158:161], v[234:237], v[40:43]
	v_mfma_f32_16x16x32_bf16 v[28:31], v[150:153], v[242:245], v[28:31]
	v_mfma_f32_16x16x32_bf16 v[24:27], v[158:161], v[242:245], v[24:27]
	v_mfma_f32_16x16x32_bf16 v[12:15], v[150:153], v[226:229], v[12:15]
	v_mfma_f32_16x16x32_bf16 v[8:11], v[158:161], v[226:229], v[8:11]
	s_setprio 0
	s_setprio 1
	v_mfma_f32_16x16x32_bf16 v[52:55], v[166:169], v[200:203], v[52:55]
	v_mfma_f32_16x16x32_bf16 v[48:51], v[174:177], v[200:203], v[48:51]
	v_mfma_f32_16x16x32_bf16 v[36:39], v[166:169], v[230:233], v[36:39]
	v_mfma_f32_16x16x32_bf16 v[32:35], v[174:177], v[230:233], v[32:35]
	v_mfma_f32_16x16x32_bf16 v[20:23], v[166:169], v[238:241], v[20:23]
	v_mfma_f32_16x16x32_bf16 v[16:19], v[174:177], v[238:241], v[16:19]
	v_mfma_f32_16x16x32_bf16 v[4:7], v[166:169], v[246:249], v[4:7]
	v_mfma_f32_16x16x32_bf16 v[0:3], v[174:177], v[246:249], v[0:3]
	v_mfma_f32_16x16x32_bf16 v[52:55], v[170:173], v[218:221], v[52:55]
	v_mfma_f32_16x16x32_bf16 v[48:51], v[178:181], v[218:221], v[48:51]
	v_mfma_f32_16x16x32_bf16 v[36:39], v[170:173], v[234:237], v[36:39]
	v_mfma_f32_16x16x32_bf16 v[32:35], v[178:181], v[234:237], v[32:35]
	v_mfma_f32_16x16x32_bf16 v[20:23], v[170:173], v[242:245], v[20:23]
	v_mfma_f32_16x16x32_bf16 v[16:19], v[178:181], v[242:245], v[16:19]
	v_mfma_f32_16x16x32_bf16 v[4:7], v[170:173], v[226:229], v[4:7]
	v_mfma_f32_16x16x32_bf16 v[0:3], v[178:181], v[226:229], v[0:3]
	s_setprio 0
	s_barrier
	s_add_i32 s24, s24, 2
	s_add_u32 s62, s62, 0x100
	s_addc_u32 s63, s63, 0
	s_add_u32 s22, s22, 0x100
	s_addc_u32 s23, s23, 0
	s_cmp_gt_u32 s24, 29
	s_cbranch_scc0 .LBB0_381
	v_mov_b32_e32 v218, 0x2a00
	v_mov_b32_e32 v219, 0xf149f2ca
	v_mov_b32_e32 v220, 0xe00
	s_mov_b64 s[4:5], 0x80
	s_and_b64 vcc, exec, s[52:53]
	s_cbranch_vccz .LBB0_384
	s_barrier

; #define PG8_STAGE(bufoff, gbase, voff) do { _Pragma("unroll") for (int _i = 0; _i < 2; ++_i) \
;         __builtin_amdgcn_global_load_lds((const unsigned*)((const char*)(gbase) + (voff)[_i]), (PG8_LAS unsigned*)(lds + (bufoff) + ldsw + _i * 8192), 16, 0, 0); } while (0)
; #define PG8_LDA(dst, b, h) do { _Pragma("unroll") for (int m = 0; m < 4; ++m) _Pragma("unroll") for (int k = 0; k < 2; ++k) dst[m][k] = *(const PG8_LAS bf16x8*)(lds + PG8_SA(b, h) + aoff + m * 2048 + k * 1024); } while (0)
; #define PG8_LDB(dst, b, h) do { _Pragma("unroll") for (int n = 0; n < 2; ++n) _Pragma("unroll") for (int k = 0; k < 2; ++k) dst[n][k] = *(const PG8_LAS bf16x8*)(lds + PG8_SB(b, h) + boff + n * 2048 + k * 1024); } while (0)
; #define PG8_MMA(ai, bj, At, Bt) do { __builtin_amdgcn_s_setprio(1); _Pragma("unroll") for (int m = 0; m < 4; ++m) _Pragma("unroll") for (int n = 0; n < 2; ++n) _Pragma("unroll") for (int k = 0; k < 2; ++k) \
;         acc[ai][bj][m][n] = __builtin_amdgcn_mfma_f32_16x16x32_bf16(Bt[n][k], At[m][k], acc[ai][bj][m][n], 0, 0, 0); __builtin_amdgcn_s_setprio(0); } while (0)
; #define PG8_WAIT_V(n) asm volatile("s_waitcnt vmcnt(" #n ")" ::: "memory")
; #define PG8_WAIT_L(n) asm volatile("s_waitcnt lgkmcnt(" #n ")" ::: "memory")
; template <class Epi, class Sched, bool ALIGN_EPI = true, bool SP2 = true>
; __device__ __forceinline__ void gemm_phase(PG8_LAS unsigned char* lds, const Gemm g, const Sched& S, const Epi& E, const int tid) {
;     ...
;             const bool last = (t == nt - 2);
;             const char* a1 = cA + (size_t)(t + 1) * kstep;
;             const char* a2 = last ? nA : cA + (size_t)(t + 2) * kstep; const char* b2 = last ? nB : cB + (size_t)(t + 2) * kstep;
;             const char* a3 = a2 + kstep; const char* b3 = b2 + kstep;
;             if (last && has_next) S.a_ready(nxt);
;             if constexpr (SP2) {
;             PG8_LDB(B0, 0, 0); PG8_LDB(B1, 0, 1); PG8_SCHED; PG8_LDA(At, 0, 0); PG8_STAGE(PG8_SA(1, 1), a1 + hstepA, voffA);
;             PG8_WAIT_V(8); PG8_WAIT_L(0); PG8_BAR; PG8_MMA(0, 0, At, B0); PG8_MMA(0, 1, At, B1); PG8_BAR; PG8_SCHED;
;             PG8_LDA(At, 0, 1); PG8_STAGE(PG8_SB(0, 0), b2, voffB); PG8_STAGE(PG8_SB(0, 1), b2 + hstepB, voffB); PG8_STAGE(PG8_SA(0, 0), a2, voffA);
;             PG8_WAIT_V(8); PG8_WAIT_L(0); PG8_BAR; PG8_MMA(1, 0, At, B0); PG8_MMA(1, 1, At, B1); PG8_BAR; PG8_SCHED;
.LBB0_1077:
	s_add_i32 s63, s82, 2
	s_add_u32 s83, s80, 0xfff80080
	s_addc_u32 s84, s81, -1
	s_add_i32 vcc_lo, 0, 0x10000
	s_cmp_eq_u32 s29, s82
	s_cselect_b32 s85, s67, s84
	s_cselect_b32 s84, s66, s83
	v_add_u32_e32 v96, vcc_lo, v141
	s_cselect_b32 s83, s69, s61
	s_cselect_b32 s82, s68, s59
	s_add_i32 s30, 0, 0x14000
	ds_read_b128 v[146:149], v96
	ds_read_b128 v[150:153], v96 offset:1024
	ds_read_b128 v[154:157], v96 offset:2048
	ds_read_b128 v[158:161], v96 offset:3072
	v_add_u32_e32 v96, s30, v141
	ds_read_b128 v[162:165], v96
	ds_read_b128 v[166:169], v96 offset:1024
	ds_read_b128 v[170:173], v96 offset:2048
	ds_read_b128 v[174:177], v96 offset:3072
	s_add_i32 m0, s25, 0xc000
	ds_read_b128 v[178:181], v145
	ds_read_b128 v[182:185], v145 offset:1024
	ds_read_b128 v[186:189], v145 offset:2048
	ds_read_b128 v[190:193], v145 offset:3072
	ds_read_b128 v[194:197], v145 offset:4096
	ds_read_b128 v[200:203], v145 offset:5120
	ds_read_b128 v[206:209], v145 offset:6144
	ds_read_b128 v[210:213], v145 offset:7168
	global_load_lds_dwordx4 v136, s[80:81]
	s_add_i32 m0, s25, 0xe000
	s_nop 0
	global_load_lds_dwordx4 v138, s[80:81]
	s_waitcnt vmcnt(8)
	s_waitcnt lgkmcnt(0)
	s_barrier
	s_setprio 1
	s_waitcnt lgkmcnt(0)
	v_mfma_f32_16x16x32_bf16 v[92:95], v[146:149], v[178:181], v[92:95]
	v_mfma_f32_16x16x32_bf16 v[130:133], v[154:157], v[178:181], v[130:133]
	ds_read_b128 v[224:227], v145 offset:16384
	v_mfma_f32_16x16x32_bf16 v[126:129], v[146:149], v[186:189], v[126:129]
	v_mfma_f32_16x16x32_bf16 v[122:125], v[154:157], v[186:189], v[122:125]
	v_mfma_f32_16x16x32_bf16 v[118:121], v[146:149], v[194:197], v[118:121]
	v_mfma_f32_16x16x32_bf16 v[110:113], v[154:157], v[194:197], v[110:113]
	ds_read_b128 v[228:231], v145 offset:17408
	v_mfma_f32_16x16x32_bf16 v[76:79], v[146:149], v[206:209], v[76:79]
	v_mfma_f32_16x16x32_bf16 v[72:75], v[154:157], v[206:209], v[72:75]
	v_mfma_f32_16x16x32_bf16 v[92:95], v[150:153], v[182:185], v[92:95]
	v_mfma_f32_16x16x32_bf16 v[130:133], v[158:161], v[182:185], v[130:133]
	ds_read_b128 v[232:235], v145 offset:18432
	v_mfma_f32_16x16x32_bf16 v[126:129], v[150:153], v[190:193], v[126:129]
	v_mfma_f32_16x16x32_bf16 v[122:125], v[158:161], v[190:193], v[122:125]
	v_mfma_f32_16x16x32_bf16 v[118:121], v[150:153], v[200:203], v[118:121]
	v_mfma_f32_16x16x32_bf16 v[110:113], v[158:161], v[200:203], v[110:113]
	ds_read_b128 v[236:239], v145 offset:19456
	v_mfma_f32_16x16x32_bf16 v[76:79], v[150:153], v[210:213], v[76:79]
	v_mfma_f32_16x16x32_bf16 v[72:75], v[158:161], v[210:213], v[72:75]
	s_setprio 0
	s_setprio 1
	v_mfma_f32_16x16x32_bf16 v[88:91], v[162:165], v[178:181], v[88:91]
	v_mfma_f32_16x16x32_bf16 v[84:87], v[170:173], v[178:181], v[84:87]
	ds_read_b128 v[240:243], v145 offset:20480
	v_mfma_f32_16x16x32_bf16 v[114:117], v[162:165], v[186:189], v[114:117]
	v_mfma_f32_16x16x32_bf16 v[106:109], v[170:173], v[186:189], v[106:109]
	v_mfma_f32_16x16x32_bf16 v[102:105], v[162:165], v[194:197], v[102:105]
	v_mfma_f32_16x16x32_bf16 v[80:83], v[170:173], v[194:197], v[80:83]
	ds_read_b128 v[244:247], v145 offset:21504
	v_mfma_f32_16x16x32_bf16 v[68:71], v[162:165], v[206:209], v[68:71]
	v_mfma_f32_16x16x32_bf16 v[64:67], v[170:173], v[206:209], v[64:67]
	v_mfma_f32_16x16x32_bf16 v[88:91], v[166:169], v[182:185], v[88:91]
	v_mfma_f32_16x16x32_bf16 v[84:87], v[174:177], v[182:185], v[84:87]
	ds_read_b128 v[248:251], v145 offset:22528
	v_mfma_f32_16x16x32_bf16 v[114:117], v[166:169], v[190:193], v[114:117]
	v_mfma_f32_16x16x32_bf16 v[106:109], v[174:177], v[190:193], v[106:109]
	v_mfma_f32_16x16x32_bf16 v[102:105], v[166:169], v[200:203], v[102:105]
	v_mfma_f32_16x16x32_bf16 v[80:83], v[174:177], v[200:203], v[80:83]
	v_mfma_f32_16x16x32_bf16 v[68:71], v[166:169], v[210:213], v[68:71]
	v_mfma_f32_16x16x32_bf16 v[64:67], v[174:177], v[210:213], v[64:67]
	s_setprio 0
	s_barrier
	s_add_i32 s31, vcc_lo, s24
	s_mov_b32 m0, s31
	ds_read_b128 v[210:213], v145 offset:23552
	global_load_lds_dwordx4 v100, s[82:83]
	s_add_i32 m0, s31, 0x2000
	s_add_u32 vcc_lo, s82, 0x80000
	s_addc_u32 vcc_hi, s83, 0
	s_add_i32 s30, s30, s24
	global_load_lds_dwordx4 v134, s[82:83]
	s_mov_b32 m0, s30
	s_nop 0
	global_load_lds_dwordx4 v100, vcc
	s_add_i32 m0, s30, 0x2000
	s_nop 0
	global_load_lds_dwordx4 v134, vcc
	s_mov_b32 m0, s25
	s_nop 0
	global_load_lds_dwordx4 v100, s[84:85]
	s_mov_b32 m0, s49
	s_nop 0
	global_load_lds_dwordx4 v134, s[84:85]
	s_waitcnt vmcnt(6)
	s_waitcnt lgkmcnt(0)
	s_barrier
	s_setprio 1
	s_waitcnt lgkmcnt(0)
	v_mfma_f32_16x16x32_bf16 v[56:59], v[146:149], v[224:227], v[56:59]
	v_mfma_f32_16x16x32_bf16 v[60:63], v[154:157], v[224:227], v[60:63]
	v_mfma_f32_16x16x32_bf16 v[44:47], v[146:149], v[232:235], v[44:47]
	v_mfma_f32_16x16x32_bf16 v[40:43], v[154:157], v[232:235], v[40:43]
	v_mfma_f32_16x16x32_bf16 v[28:31], v[146:149], v[240:243], v[28:31]
	v_mfma_f32_16x16x32_bf16 v[24:27], v[154:157], v[240:243], v[24:27]
	v_mfma_f32_16x16x32_bf16 v[12:15], v[146:149], v[248:251], v[12:15]
	v_mfma_f32_16x16x32_bf16 v[8:11], v[154:157], v[248:251], v[8:11]
	v_mfma_f32_16x16x32_bf16 v[56:59], v[150:153], v[228:231], v[56:59]
	v_mfma_f32_16x16x32_bf16 v[60:63], v[158:161], v[228:231], v[60:63]
	v_mfma_f32_16x16x32_bf16 v[44:47], v[150:153], v[236:239], v[44:47]
	v_mfma_f32_16x16x32_bf16 v[40:43], v[158:161], v[236:239], v[40:43]
	v_mfma_f32_16x16x32_bf16 v[28:31], v[150:153], v[244:247], v[28:31]
	v_mfma_f32_16x16x32_bf16 v[24:27], v[158:161], v[244:247], v[24:27]
	v_mfma_f32_16x16x32_bf16 v[12:15], v[150:153], v[210:213], v[12:15]
	v_mfma_f32_16x16x32_bf16 v[8:11], v[158:161], v[210:213], v[8:11]
	s_setprio 0
	s_setprio 1
	v_mfma_f32_16x16x32_bf16 v[52:55], v[162:165], v[224:227], v[52:55]
	v_mfma_f32_16x16x32_bf16 v[48:51], v[170:173], v[224:227], v[48:51]
	v_mfma_f32_16x16x32_bf16 v[36:39], v[162:165], v[232:235], v[36:39]
	v_mfma_f32_16x16x32_bf16 v[32:35], v[170:173], v[232:235], v[32:35]
	v_mfma_f32_16x16x32_bf16 v[20:23], v[162:165], v[240:243], v[20:23]
	v_mfma_f32_16x16x32_bf16 v[16:19], v[170:173], v[240:243], v[16:19]
	v_mfma_f32_16x16x32_bf16 v[4:7], v[162:165], v[248:251], v[4:7]
	v_mfma_f32_16x16x32_bf16 v[0:3], v[170:173], v[248:251], v[0:3]
	v_mfma_f32_16x16x32_bf16 v[52:55], v[166:169], v[228:231], v[52:55]
	v_mfma_f32_16x16x32_bf16 v[48:51], v[174:177], v[228:231], v[48:51]
	v_mfma_f32_16x16x32_bf16 v[36:39], v[166:169], v[236:239], v[36:39]
	v_mfma_f32_16x16x32_bf16 v[32:35], v[174:177], v[236:239], v[32:35]
	v_mfma_f32_16x16x32_bf16 v[20:23], v[166:169], v[244:247], v[20:23]
	v_mfma_f32_16x16x32_bf16 v[16:19], v[174:177], v[244:247], v[16:19]
	v_mfma_f32_16x16x32_bf16 v[4:7], v[166:169], v[210:213], v[4:7]
	v_mfma_f32_16x16x32_bf16 v[0:3], v[174:177], v[210:213], v[0:3]
	s_setprio 0
	s_barrier
; #define PG8_STAGE(bufoff, gbase, voff) do { _Pragma("unroll") for (int _i = 0; _i < 2; ++_i) \
;         __builtin_amdgcn_global_load_lds((const unsigned*)((const char*)(gbase) + (voff)[_i]), (PG8_LAS unsigned*)(lds + (bufoff) + ldsw + _i * 8192), 16, 0, 0); } while (0)
; #define PG8_LDA(dst, b, h) do { _Pragma("unroll") for (int m = 0; m < 4; ++m) _Pragma("unroll") for (int k = 0; k < 2; ++k) dst[m][k] = *(const PG8_LAS bf16x8*)(lds + PG8_SA(b, h) + aoff + m * 2048 + k * 1024); } while (0)
; #define PG8_LDB(dst, b, h) do { _Pragma("unroll") for (int n = 0; n < 2; ++n) _Pragma("unroll") for (int k = 0; k < 2; ++k) dst[n][k] = *(const PG8_LAS bf16x8*)(lds + PG8_SB(b, h) + boff + n * 2048 + k * 1024); } while (0)
; #define PG8_MMA(ai, bj, At, Bt) do { __builtin_amdgcn_s_setprio(1); _Pragma("unroll") for (int m = 0; m < 4; ++m) _Pragma("unroll") for (int n = 0; n < 2; ++n) _Pragma("unroll") for (int k = 0; k < 2; ++k) \
;         acc[ai][bj][m][n] = __builtin_amdgcn_mfma_f32_16x16x32_bf16(Bt[n][k], At[m][k], acc[ai][bj][m][n], 0, 0, 0); __builtin_amdgcn_s_setprio(0); } while (0)
; #define PG8_WAIT_V(n) asm volatile("s_waitcnt vmcnt(" #n ")" ::: "memory")
; #define PG8_WAIT_L(n) asm volatile("s_waitcnt lgkmcnt(" #n ")" ::: "memory")
; #define PG8_BAR __builtin_amdgcn_s_barrier()
; #define PG8_SCHED __builtin_amdgcn_sched_barrier(0)
; template <class Epi, class Sched, bool ALIGN_EPI = true, bool SP2 = true>
; __device__ __forceinline__ void gemm_phase(PG8_LAS unsigned char* lds, const Gemm g, const Sched& S, const Epi& E, const int tid) {
;     ...
;             PG8_LDB(B0, 1, 0); PG8_LDB(B1, 1, 1); PG8_SCHED; PG8_LDA(At, 1, 0); PG8_STAGE(PG8_SA(0, 1), a2 + hstepA, voffA);
;             PG8_WAIT_V(8); PG8_WAIT_L(0); PG8_BAR; PG8_MMA(0, 0, At, B0); PG8_MMA(0, 1, At, B1); PG8_BAR; PG8_SCHED;
;             PG8_LDA(At, 1, 1); PG8_STAGE(PG8_SB(1, 0), b3, voffB); PG8_STAGE(PG8_SB(1, 1), b3 + hstepB, voffB); PG8_STAGE(PG8_SA(1, 0), a3, voffA);
;             PG8_WAIT_V(8); PG8_WAIT_L(0); PG8_BAR; PG8_MMA(1, 0, At, B0); PG8_MMA(1, 1, At, B1); PG8_BAR; PG8_SCHED;
	s_add_i32 s30, 0, 0x18000
	v_add_u32_e32 v96, s30, v141
	s_add_i32 s31, 0, 0x1c000
	ds_read_b128 v[146:149], v96
	ds_read_b128 v[150:153], v96 offset:1024
	ds_read_b128 v[154:157], v96 offset:2048
	ds_read_b128 v[158:161], v96 offset:3072
	v_add_u32_e32 v96, s31, v141
	ds_read_b128 v[162:165], v96
	ds_read_b128 v[166:169], v96 offset:1024
	ds_read_b128 v[170:173], v96 offset:2048
	ds_read_b128 v[174:177], v96 offset:3072
	s_add_u32 s84, s84, 0x80000
	s_addc_u32 s85, s85, 0
	s_mov_b32 m0, s51
	ds_read_b128 v[178:181], v145 offset:32768
	ds_read_b128 v[182:185], v145 offset:33792
	ds_read_b128 v[186:189], v145 offset:34816
	ds_read_b128 v[190:193], v145 offset:35840
	ds_read_b128 v[194:197], v145 offset:36864
	ds_read_b128 v[200:203], v145 offset:37888
	ds_read_b128 v[206:209], v145 offset:38912
	ds_read_b128 v[210:213], v145 offset:39936
	global_load_lds_dwordx4 v100, s[84:85]
	s_mov_b32 m0, s76
	s_nop 0
	global_load_lds_dwordx4 v134, s[84:85]
	s_waitcnt vmcnt(8)
	s_waitcnt lgkmcnt(0)
	s_barrier
	s_setprio 1
	s_waitcnt lgkmcnt(0)
	v_mfma_f32_16x16x32_bf16 v[92:95], v[146:149], v[178:181], v[92:95]
	v_mfma_f32_16x16x32_bf16 v[130:133], v[154:157], v[178:181], v[130:133]
	ds_read_b128 v[224:227], v145 offset:49152
	v_mfma_f32_16x16x32_bf16 v[126:129], v[146:149], v[186:189], v[126:129]
	v_mfma_f32_16x16x32_bf16 v[122:125], v[154:157], v[186:189], v[122:125]
	v_mfma_f32_16x16x32_bf16 v[118:121], v[146:149], v[194:197], v[118:121]
	v_mfma_f32_16x16x32_bf16 v[110:113], v[154:157], v[194:197], v[110:113]
	ds_read_b128 v[228:231], v145 offset:50176
	v_mfma_f32_16x16x32_bf16 v[76:79], v[146:149], v[206:209], v[76:79]
	v_mfma_f32_16x16x32_bf16 v[72:75], v[154:157], v[206:209], v[72:75]
	v_mfma_f32_16x16x32_bf16 v[92:95], v[150:153], v[182:185], v[92:95]
	v_mfma_f32_16x16x32_bf16 v[130:133], v[158:161], v[182:185], v[130:133]
	ds_read_b128 v[232:235], v145 offset:51200
	v_mfma_f32_16x16x32_bf16 v[126:129], v[150:153], v[190:193], v[126:129]
	v_mfma_f32_16x16x32_bf16 v[122:125], v[158:161], v[190:193], v[122:125]
	v_mfma_f32_16x16x32_bf16 v[118:121], v[150:153], v[200:203], v[118:121]
	v_mfma_f32_16x16x32_bf16 v[110:113], v[158:161], v[200:203], v[110:113]
	ds_read_b128 v[236:239], v145 offset:52224
	v_mfma_f32_16x16x32_bf16 v[76:79], v[150:153], v[210:213], v[76:79]
	v_mfma_f32_16x16x32_bf16 v[72:75], v[158:161], v[210:213], v[72:75]
	s_setprio 0
	s_setprio 1
	v_mfma_f32_16x16x32_bf16 v[88:91], v[162:165], v[178:181], v[88:91]
	v_mfma_f32_16x16x32_bf16 v[84:87], v[170:173], v[178:181], v[84:87]
	ds_read_b128 v[240:243], v145 offset:53248
	v_mfma_f32_16x16x32_bf16 v[114:117], v[162:165], v[186:189], v[114:117]
	v_mfma_f32_16x16x32_bf16 v[106:109], v[170:173], v[186:189], v[106:109]
	v_mfma_f32_16x16x32_bf16 v[102:105], v[162:165], v[194:197], v[102:105]
	v_mfma_f32_16x16x32_bf16 v[80:83], v[170:173], v[194:197], v[80:83]
	ds_read_b128 v[244:247], v145 offset:54272
	v_mfma_f32_16x16x32_bf16 v[68:71], v[162:165], v[206:209], v[68:71]
	v_mfma_f32_16x16x32_bf16 v[64:67], v[170:173], v[206:209], v[64:67]
	v_mfma_f32_16x16x32_bf16 v[88:91], v[166:169], v[182:185], v[88:91]
	v_mfma_f32_16x16x32_bf16 v[84:87], v[174:177], v[182:185], v[84:87]
	ds_read_b128 v[248:251], v145 offset:55296
	v_mfma_f32_16x16x32_bf16 v[114:117], v[166:169], v[190:193], v[114:117]
	v_mfma_f32_16x16x32_bf16 v[106:109], v[174:177], v[190:193], v[106:109]
	v_mfma_f32_16x16x32_bf16 v[102:105], v[166:169], v[200:203], v[102:105]
	v_mfma_f32_16x16x32_bf16 v[80:83], v[174:177], v[200:203], v[80:83]
	v_mfma_f32_16x16x32_bf16 v[68:71], v[166:169], v[210:213], v[68:71]
	v_mfma_f32_16x16x32_bf16 v[64:67], v[174:177], v[210:213], v[64:67]
	s_setprio 0
	s_barrier
	s_add_i32 s30, s30, s24
	s_add_u32 s4, s82, 0x80
	s_addc_u32 s5, s83, 0
	s_mov_b32 m0, s30
	ds_read_b128 v[210:213], v145 offset:56320
	global_load_lds_dwordx4 v100, s[4:5]
	s_add_i32 m0, s30, 0x2000
	s_add_u32 s82, s82, 0x80080
	s_addc_u32 s83, s83, 0
	s_add_i32 s30, s31, s24
	global_load_lds_dwordx4 v134, s[4:5]
	s_mov_b32 m0, s30
	s_nop 0
	global_load_lds_dwordx4 v100, s[82:83]
	s_add_i32 m0, s30, 0x2000
	s_nop 0
	global_load_lds_dwordx4 v134, s[82:83]
	s_add_u32 s4, s84, 0xfff80080
	s_addc_u32 s5, s85, -1
	s_mov_b32 m0, s90
	s_nop 0
	global_load_lds_dwordx4 v100, s[4:5]
	s_mov_b32 m0, s91
	s_nop 0
	global_load_lds_dwordx4 v134, s[4:5]
	s_waitcnt vmcnt(6)
	s_waitcnt lgkmcnt(0)
	s_barrier
	s_setprio 1
	s_waitcnt lgkmcnt(0)
	v_mfma_f32_16x16x32_bf16 v[56:59], v[146:149], v[224:227], v[56:59]
	v_mfma_f32_16x16x32_bf16 v[60:63], v[154:157], v[224:227], v[60:63]
	v_mfma_f32_16x16x32_bf16 v[44:47], v[146:149], v[232:235], v[44:47]
	v_mfma_f32_16x16x32_bf16 v[40:43], v[154:157], v[232:235], v[40:43]
	v_mfma_f32_16x16x32_bf16 v[28:31], v[146:149], v[240:243], v[28:31]
	v_mfma_f32_16x16x32_bf16 v[24:27], v[154:157], v[240:243], v[24:27]
	v_mfma_f32_16x16x32_bf16 v[12:15], v[146:149], v[248:251], v[12:15]
	v_mfma_f32_16x16x32_bf16 v[8:11], v[154:157], v[248:251], v[8:11]
	v_mfma_f32_16x16x32_bf16 v[56:59], v[150:153], v[228:231], v[56:59]
	v_mfma_f32_16x16x32_bf16 v[60:63], v[158:161], v[228:231], v[60:63]
	v_mfma_f32_16x16x32_bf16 v[44:47], v[150:153], v[236:239], v[44:47]
	v_mfma_f32_16x16x32_bf16 v[40:43], v[158:161], v[236:239], v[40:43]
	v_mfma_f32_16x16x32_bf16 v[28:31], v[150:153], v[244:247], v[28:31]
	v_mfma_f32_16x16x32_bf16 v[24:27], v[158:161], v[244:247], v[24:27]
	v_mfma_f32_16x16x32_bf16 v[12:15], v[150:153], v[210:213], v[12:15]
	v_mfma_f32_16x16x32_bf16 v[8:11], v[158:161], v[210:213], v[8:11]
	s_setprio 0
	s_setprio 1
	v_mfma_f32_16x16x32_bf16 v[52:55], v[162:165], v[224:227], v[52:55]
	v_mfma_f32_16x16x32_bf16 v[48:51], v[170:173], v[224:227], v[48:51]
	v_mfma_f32_16x16x32_bf16 v[36:39], v[162:165], v[232:235], v[36:39]
	v_mfma_f32_16x16x32_bf16 v[32:35], v[170:173], v[232:235], v[32:35]
	v_mfma_f32_16x16x32_bf16 v[20:23], v[162:165], v[240:243], v[20:23]
	v_mfma_f32_16x16x32_bf16 v[16:19], v[170:173], v[240:243], v[16:19]
	v_mfma_f32_16x16x32_bf16 v[4:7], v[162:165], v[248:251], v[4:7]
	v_mfma_f32_16x16x32_bf16 v[0:3], v[170:173], v[248:251], v[0:3]
	v_mfma_f32_16x16x32_bf16 v[52:55], v[166:169], v[228:231], v[52:55]
	v_mfma_f32_16x16x32_bf16 v[48:51], v[174:177], v[228:231], v[48:51]
	v_mfma_f32_16x16x32_bf16 v[36:39], v[166:169], v[236:239], v[36:39]
	v_mfma_f32_16x16x32_bf16 v[32:35], v[174:177], v[236:239], v[32:35]
	v_mfma_f32_16x16x32_bf16 v[20:23], v[166:169], v[244:247], v[20:23]
	v_mfma_f32_16x16x32_bf16 v[16:19], v[174:177], v[244:247], v[16:19]
	v_mfma_f32_16x16x32_bf16 v[4:7], v[166:169], v[210:213], v[4:7]
	v_mfma_f32_16x16x32_bf16 v[0:3], v[174:177], v[210:213], v[0:3]
	s_setprio 0
	s_barrier
	s_add_u32 s80, s80, 0x100
	s_addc_u32 s81, s81, 0
	s_add_u32 s59, s59, 0x100
	s_addc_u32 s61, s61, 0
	s_cmp_ge_i32 s63, s57
	s_mov_b32 s82, s63
	s_cbranch_scc0 .LBB0_1077
	s_mov_b64 s[4:5], 0x80

; #define PG8_STAGE(bufoff, gbase, voff) do { _Pragma("unroll") for (int _i = 0; _i < 2; ++_i) \
;         __builtin_amdgcn_global_load_lds((const unsigned*)((const char*)(gbase) + (voff)[_i]), (PG8_LAS unsigned*)(lds + (bufoff) + ldsw + _i * 8192), 16, 0, 0); } while (0)
; #define PG8_LDA(dst, b, h) do { _Pragma("unroll") for (int m = 0; m < 4; ++m) _Pragma("unroll") for (int k = 0; k < 2; ++k) dst[m][k] = *(const PG8_LAS bf16x8*)(lds + PG8_SA(b, h) + aoff + m * 2048 + k * 1024); } while (0)
; #define PG8_LDB(dst, b, h) do { _Pragma("unroll") for (int n = 0; n < 2; ++n) _Pragma("unroll") for (int k = 0; k < 2; ++k) dst[n][k] = *(const PG8_LAS bf16x8*)(lds + PG8_SB(b, h) + boff + n * 2048 + k * 1024); } while (0)
; #define PG8_MMA(ai, bj, At, Bt) do { __builtin_amdgcn_s_setprio(1); _Pragma("unroll") for (int m = 0; m < 4; ++m) _Pragma("unroll") for (int n = 0; n < 2; ++n) _Pragma("unroll") for (int k = 0; k < 2; ++k) \
;         acc[ai][bj][m][n] = __builtin_amdgcn_mfma_f32_16x16x32_bf16(Bt[n][k], At[m][k], acc[ai][bj][m][n], 0, 0, 0); __builtin_amdgcn_s_setprio(0); } while (0)
; #define PG8_WAIT_V(n) asm volatile("s_waitcnt vmcnt(" #n ")" ::: "memory")
; #define PG8_BAR __builtin_amdgcn_s_barrier()
; template <class Epi, class Sched, bool ALIGN_EPI = true, bool SP2 = true>
; __device__ __forceinline__ void gemm_phase(PG8_LAS unsigned char* lds, const Gemm g, const Sched& S, const Epi& E, const int tid) {
;     ...
;         for (int t = 0; t < nt; t += 2) {
;             const bool last = (t == nt - 2);
;             const char* a1 = cA + (size_t)(t + 1) * kstep;
;             const char* a2 = last ? nA : cA + (size_t)(t + 2) * kstep; const char* b2 = last ? nB : cB + (size_t)(t + 2) * kstep;
;             const char* a3 = a2 + kstep; const char* b3 = b2 + kstep;
;             if (last && has_next) S.a_ready(nxt);
;             if constexpr (SP2) {
;             PG8_LDB(B0, 0, 0); PG8_LDB(B1, 0, 1); PG8_SCHED; PG8_LDA(At, 0, 0); PG8_STAGE(PG8_SA(1, 1), a1 + hstepA, voffA);
;             PG8_WAIT_V(8); PG8_WAIT_L(0); PG8_BAR; PG8_MMA(0, 0, At, B0); PG8_MMA(0, 1, At, B1); PG8_BAR; PG8_SCHED;
;             PG8_LDA(At, 0, 1); PG8_STAGE(PG8_SB(0, 0), b2, voffB); PG8_STAGE(PG8_SB(0, 1), b2 + hstepB, voffB); PG8_STAGE(PG8_SA(0, 0), a2, voffA);
;             PG8_WAIT_V(8); PG8_WAIT_L(0); PG8_BAR; PG8_MMA(1, 0, At, B0); PG8_MMA(1, 1, At, B1); PG8_BAR; PG8_SCHED;
.LBB0_1523:
	s_add_i32 vcc_lo, s72, 2
	s_add_u32 s70, s82, 0x100
	s_addc_u32 s71, s83, 0
	s_add_i32 s30, 0, 0x10000
	s_cmp_eq_u32 s29, s72
	s_cselect_b32 s81, s63, s71
	s_cselect_b32 s80, s62, s70
	v_add_u32_e32 v96, s30, v141
	s_cselect_b32 s73, s65, s59
	s_cselect_b32 s72, s64, s57
	s_add_i32 s31, 0, 0x14000
	ds_read_b128 v[146:149], v96
	ds_read_b128 v[150:153], v96 offset:1024
	ds_read_b128 v[154:157], v96 offset:2048
	ds_read_b128 v[158:161], v96 offset:3072
	v_add_u32_e32 v96, s31, v141
	ds_read_b128 v[162:165], v96
	ds_read_b128 v[166:169], v96 offset:1024
	ds_read_b128 v[170:173], v96 offset:2048
	ds_read_b128 v[174:177], v96 offset:3072
	s_add_i32 m0, s23, 0xc000
	ds_read_b128 v[178:181], v145
	ds_read_b128 v[182:185], v145 offset:1024
	ds_read_b128 v[186:189], v145 offset:2048
	ds_read_b128 v[190:193], v145 offset:3072
	ds_read_b128 v[194:197], v145 offset:4096
	ds_read_b128 v[200:203], v145 offset:5120
	ds_read_b128 v[206:209], v145 offset:6144
	ds_read_b128 v[210:213], v145 offset:7168
	global_load_lds_dwordx4 v136, s[82:83]
	s_add_i32 m0, s23, 0xe000
	s_nop 0
	global_load_lds_dwordx4 v138, s[82:83]
	s_waitcnt vmcnt(8)
	s_waitcnt lgkmcnt(0)
	s_barrier
	s_setprio 1
	s_waitcnt lgkmcnt(0)
	v_mfma_f32_16x16x32_bf16 v[52:55], v[146:149], v[178:181], v[52:55]
	v_mfma_f32_16x16x32_bf16 v[56:59], v[154:157], v[178:181], v[56:59]
	ds_read_b128 v[224:227], v145 offset:16384
	v_mfma_f32_16x16x32_bf16 v[104:107], v[146:149], v[186:189], v[104:107]
	v_mfma_f32_16x16x32_bf16 v[84:87], v[154:157], v[186:189], v[84:87]
	v_mfma_f32_16x16x32_bf16 v[110:113], v[146:149], v[194:197], v[110:113]
	v_mfma_f32_16x16x32_bf16 v[98:101], v[154:157], v[194:197], v[100:103]
	ds_read_b128 v[228:231], v145 offset:17408
	v_mfma_f32_16x16x32_bf16 v[88:91], v[146:149], v[206:209], v[88:91]
	v_mfma_f32_16x16x32_bf16 v[80:83], v[154:157], v[206:209], v[80:83]
	v_mfma_f32_16x16x32_bf16 v[52:55], v[150:153], v[182:185], v[52:55]
	v_mfma_f32_16x16x32_bf16 v[56:59], v[158:161], v[182:185], v[56:59]
	ds_read_b128 v[232:235], v145 offset:18432
	v_mfma_f32_16x16x32_bf16 v[104:107], v[150:153], v[190:193], v[104:107]
	v_mfma_f32_16x16x32_bf16 v[84:87], v[158:161], v[190:193], v[84:87]
	v_mfma_f32_16x16x32_bf16 v[110:113], v[150:153], v[200:203], v[110:113]
	v_mfma_f32_16x16x32_bf16 v[98:101], v[158:161], v[200:203], v[98:101]
	ds_read_b128 v[236:239], v145 offset:19456
	v_mfma_f32_16x16x32_bf16 v[88:91], v[150:153], v[210:213], v[88:91]
	v_mfma_f32_16x16x32_bf16 v[80:83], v[158:161], v[210:213], v[80:83]
	s_setprio 0
	s_setprio 1
	v_mfma_f32_16x16x32_bf16 v[48:51], v[162:165], v[178:181], v[48:51]
	v_mfma_f32_16x16x32_bf16 v[44:47], v[170:173], v[178:181], v[44:47]
	ds_read_b128 v[240:243], v145 offset:20480
	v_mfma_f32_16x16x32_bf16 v[76:79], v[162:165], v[186:189], v[76:79]
	v_mfma_f32_16x16x32_bf16 v[68:71], v[170:173], v[186:189], v[68:71]
	v_mfma_f32_16x16x32_bf16 v[130:133], v[162:165], v[194:197], v[130:133]
	v_mfma_f32_16x16x32_bf16 v[92:95], v[170:173], v[194:197], v[92:95]
	ds_read_b128 v[244:247], v145 offset:21504
	v_mfma_f32_16x16x32_bf16 v[72:75], v[162:165], v[206:209], v[72:75]
	v_mfma_f32_16x16x32_bf16 v[64:67], v[170:173], v[206:209], v[64:67]
	v_mfma_f32_16x16x32_bf16 v[48:51], v[166:169], v[182:185], v[48:51]
	v_mfma_f32_16x16x32_bf16 v[44:47], v[174:177], v[182:185], v[44:47]
	ds_read_b128 v[248:251], v145 offset:22528
	v_mfma_f32_16x16x32_bf16 v[76:79], v[166:169], v[190:193], v[76:79]
	v_mfma_f32_16x16x32_bf16 v[68:71], v[174:177], v[190:193], v[68:71]
	v_mfma_f32_16x16x32_bf16 v[130:133], v[166:169], v[200:203], v[130:133]
	v_mfma_f32_16x16x32_bf16 v[92:95], v[174:177], v[200:203], v[92:95]
	v_mfma_f32_16x16x32_bf16 v[72:75], v[166:169], v[210:213], v[72:75]
	v_mfma_f32_16x16x32_bf16 v[64:67], v[174:177], v[210:213], v[64:67]
	s_setprio 0
	s_barrier
	s_add_i32 s30, s30, s22
	s_mov_b32 m0, s30
	ds_read_b128 v[210:213], v145 offset:23552
	global_load_lds_dwordx4 v108, s[72:73]
	s_add_i32 m0, s30, 0x2000
	s_add_u32 s82, s72, 0x160000
	s_addc_u32 s83, s73, 0
	s_add_i32 s30, s31, s22
	global_load_lds_dwordx4 v134, s[72:73]
	s_mov_b32 m0, s30
	s_nop 0
	global_load_lds_dwordx4 v108, s[82:83]
	s_add_i32 m0, s30, 0x2000
	s_nop 0
	global_load_lds_dwordx4 v134, s[82:83]
	s_mov_b32 m0, s23
	s_nop 0
	global_load_lds_dwordx4 v108, s[80:81]
	s_mov_b32 m0, s24
	s_nop 0
	global_load_lds_dwordx4 v134, s[80:81]
	s_waitcnt vmcnt(6)
	s_waitcnt lgkmcnt(0)
	s_barrier
	s_setprio 1
	s_waitcnt lgkmcnt(0)
	v_mfma_f32_16x16x32_bf16 v[126:129], v[146:149], v[224:227], v[126:129]
	v_mfma_f32_16x16x32_bf16 v[122:125], v[154:157], v[224:227], v[122:125]
	v_mfma_f32_16x16x32_bf16 v[60:63], v[146:149], v[232:235], v[60:63]
	v_mfma_f32_16x16x32_bf16 v[40:43], v[154:157], v[232:235], v[40:43]
	v_mfma_f32_16x16x32_bf16 v[28:31], v[146:149], v[240:243], v[28:31]
	v_mfma_f32_16x16x32_bf16 v[24:27], v[154:157], v[240:243], v[24:27]
	v_mfma_f32_16x16x32_bf16 v[12:15], v[146:149], v[248:251], v[12:15]
	v_mfma_f32_16x16x32_bf16 v[8:11], v[154:157], v[248:251], v[8:11]
	v_mfma_f32_16x16x32_bf16 v[126:129], v[150:153], v[228:231], v[126:129]
	v_mfma_f32_16x16x32_bf16 v[122:125], v[158:161], v[228:231], v[122:125]
	v_mfma_f32_16x16x32_bf16 v[60:63], v[150:153], v[236:239], v[60:63]
	v_mfma_f32_16x16x32_bf16 v[40:43], v[158:161], v[236:239], v[40:43]
	v_mfma_f32_16x16x32_bf16 v[28:31], v[150:153], v[244:247], v[28:31]
	v_mfma_f32_16x16x32_bf16 v[24:27], v[158:161], v[244:247], v[24:27]
	v_mfma_f32_16x16x32_bf16 v[12:15], v[150:153], v[210:213], v[12:15]
	v_mfma_f32_16x16x32_bf16 v[8:11], v[158:161], v[210:213], v[8:11]
	s_setprio 0
	s_setprio 1
	v_mfma_f32_16x16x32_bf16 v[118:121], v[162:165], v[224:227], v[118:121]
	v_mfma_f32_16x16x32_bf16 v[114:117], v[170:173], v[224:227], v[114:117]
	v_mfma_f32_16x16x32_bf16 v[36:39], v[162:165], v[232:235], v[36:39]
	v_mfma_f32_16x16x32_bf16 v[32:35], v[170:173], v[232:235], v[32:35]
	v_mfma_f32_16x16x32_bf16 v[20:23], v[162:165], v[240:243], v[20:23]
	v_mfma_f32_16x16x32_bf16 v[16:19], v[170:173], v[240:243], v[16:19]
	v_mfma_f32_16x16x32_bf16 v[4:7], v[162:165], v[248:251], v[4:7]
	v_mfma_f32_16x16x32_bf16 v[0:3], v[170:173], v[248:251], v[0:3]
	v_mfma_f32_16x16x32_bf16 v[118:121], v[166:169], v[228:231], v[118:121]
	v_mfma_f32_16x16x32_bf16 v[114:117], v[174:177], v[228:231], v[114:117]
	v_mfma_f32_16x16x32_bf16 v[36:39], v[166:169], v[236:239], v[36:39]
	v_mfma_f32_16x16x32_bf16 v[32:35], v[174:177], v[236:239], v[32:35]
	v_mfma_f32_16x16x32_bf16 v[20:23], v[166:169], v[244:247], v[20:23]
	v_mfma_f32_16x16x32_bf16 v[16:19], v[174:177], v[244:247], v[16:19]
	v_mfma_f32_16x16x32_bf16 v[4:7], v[166:169], v[210:213], v[4:7]
	v_mfma_f32_16x16x32_bf16 v[0:3], v[174:177], v[210:213], v[0:3]
	s_setprio 0
	s_barrier
; #define PG8_STAGE(bufoff, gbase, voff) do { _Pragma("unroll") for (int _i = 0; _i < 2; ++_i) \
;         __builtin_amdgcn_global_load_lds((const unsigned*)((const char*)(gbase) + (voff)[_i]), (PG8_LAS unsigned*)(lds + (bufoff) + ldsw + _i * 8192), 16, 0, 0); } while (0)
; #define PG8_LDA(dst, b, h) do { _Pragma("unroll") for (int m = 0; m < 4; ++m) _Pragma("unroll") for (int k = 0; k < 2; ++k) dst[m][k] = *(const PG8_LAS bf16x8*)(lds + PG8_SA(b, h) + aoff + m * 2048 + k * 1024); } while (0)
; #define PG8_LDB(dst, b, h) do { _Pragma("unroll") for (int n = 0; n < 2; ++n) _Pragma("unroll") for (int k = 0; k < 2; ++k) dst[n][k] = *(const PG8_LAS bf16x8*)(lds + PG8_SB(b, h) + boff + n * 2048 + k * 1024); } while (0)
; #define PG8_MMA(ai, bj, At, Bt) do { __builtin_amdgcn_s_setprio(1); _Pragma("unroll") for (int m = 0; m < 4; ++m) _Pragma("unroll") for (int n = 0; n < 2; ++n) _Pragma("unroll") for (int k = 0; k < 2; ++k) \
;         acc[ai][bj][m][n] = __builtin_amdgcn_mfma_f32_16x16x32_bf16(Bt[n][k], At[m][k], acc[ai][bj][m][n], 0, 0, 0); __builtin_amdgcn_s_setprio(0); } while (0)
; #define PG8_WAIT_V(n) asm volatile("s_waitcnt vmcnt(" #n ")" ::: "memory")
; #define PG8_WAIT_L(n) asm volatile("s_waitcnt lgkmcnt(" #n ")" ::: "memory")
; #define PG8_BAR __builtin_amdgcn_s_barrier()
; #define PG8_SCHED __builtin_amdgcn_sched_barrier(0)
; template <class Epi, class Sched, bool ALIGN_EPI = true, bool SP2 = true>
; __device__ __forceinline__ void gemm_phase(PG8_LAS unsigned char* lds, const Gemm g, const Sched& S, const Epi& E, const int tid) {
;     ...
;             PG8_LDB(B0, 1, 0); PG8_LDB(B1, 1, 1); PG8_SCHED; PG8_LDA(At, 1, 0); PG8_STAGE(PG8_SA(0, 1), a2 + hstepA, voffA);
;             PG8_WAIT_V(8); PG8_WAIT_L(0); PG8_BAR; PG8_MMA(0, 0, At, B0); PG8_MMA(0, 1, At, B1); PG8_BAR; PG8_SCHED;
;             PG8_LDA(At, 1, 1); PG8_STAGE(PG8_SB(1, 0), b3, voffB); PG8_STAGE(PG8_SB(1, 1), b3 + hstepB, voffB); PG8_STAGE(PG8_SA(1, 0), a3, voffA);
;             PG8_WAIT_V(8); PG8_WAIT_L(0); PG8_BAR; PG8_MMA(1, 0, At, B0); PG8_MMA(1, 1, At, B1); PG8_BAR; PG8_SCHED;
	s_add_i32 s30, 0, 0x18000
	v_add_u32_e32 v96, s30, v141
	s_add_i32 s31, 0, 0x1c000
	ds_read_b128 v[146:149], v96
	ds_read_b128 v[150:153], v96 offset:1024
	ds_read_b128 v[154:157], v96 offset:2048
	ds_read_b128 v[158:161], v96 offset:3072
	v_add_u32_e32 v96, s31, v141
	ds_read_b128 v[162:165], v96
	ds_read_b128 v[166:169], v96 offset:1024
	ds_read_b128 v[170:173], v96 offset:2048
	ds_read_b128 v[174:177], v96 offset:3072
	s_add_u32 s80, s80, 0x160000
	s_addc_u32 s81, s81, 0
	s_mov_b32 m0, s25
	ds_read_b128 v[178:181], v145 offset:32768
	ds_read_b128 v[182:185], v145 offset:33792
	ds_read_b128 v[186:189], v145 offset:34816
	ds_read_b128 v[190:193], v145 offset:35840
	ds_read_b128 v[194:197], v145 offset:36864
	ds_read_b128 v[200:203], v145 offset:37888
	ds_read_b128 v[206:209], v145 offset:38912
	ds_read_b128 v[210:213], v145 offset:39936
	global_load_lds_dwordx4 v108, s[80:81]
	s_mov_b32 m0, s49
	s_nop 0
	global_load_lds_dwordx4 v134, s[80:81]
	s_waitcnt vmcnt(8)
	s_waitcnt lgkmcnt(0)
	s_barrier
	s_setprio 1
	s_waitcnt lgkmcnt(0)
	v_mfma_f32_16x16x32_bf16 v[52:55], v[146:149], v[178:181], v[52:55]
	v_mfma_f32_16x16x32_bf16 v[56:59], v[154:157], v[178:181], v[56:59]
	ds_read_b128 v[224:227], v145 offset:49152
	v_mfma_f32_16x16x32_bf16 v[102:105], v[146:149], v[186:189], v[104:107]
	v_mfma_f32_16x16x32_bf16 v[84:87], v[154:157], v[186:189], v[84:87]
	v_mfma_f32_16x16x32_bf16 v[110:113], v[146:149], v[194:197], v[110:113]
	v_mfma_f32_16x16x32_bf16 v[98:101], v[154:157], v[194:197], v[98:101]
	ds_read_b128 v[228:231], v145 offset:50176
	v_mfma_f32_16x16x32_bf16 v[88:91], v[146:149], v[206:209], v[88:91]
	v_mfma_f32_16x16x32_bf16 v[80:83], v[154:157], v[206:209], v[80:83]
	v_mfma_f32_16x16x32_bf16 v[52:55], v[150:153], v[182:185], v[52:55]
	v_mfma_f32_16x16x32_bf16 v[56:59], v[158:161], v[182:185], v[56:59]
	ds_read_b128 v[232:235], v145 offset:51200
	v_mfma_f32_16x16x32_bf16 v[104:107], v[150:153], v[190:193], v[102:105]
	v_mfma_f32_16x16x32_bf16 v[84:87], v[158:161], v[190:193], v[84:87]
	v_mfma_f32_16x16x32_bf16 v[110:113], v[150:153], v[200:203], v[110:113]
	v_mfma_f32_16x16x32_bf16 v[100:103], v[158:161], v[200:203], v[98:101]
	ds_read_b128 v[236:239], v145 offset:52224
	v_mfma_f32_16x16x32_bf16 v[88:91], v[150:153], v[210:213], v[88:91]
	v_mfma_f32_16x16x32_bf16 v[80:83], v[158:161], v[210:213], v[80:83]
	s_setprio 0
	s_setprio 1
	v_mfma_f32_16x16x32_bf16 v[48:51], v[162:165], v[178:181], v[48:51]
	v_mfma_f32_16x16x32_bf16 v[44:47], v[170:173], v[178:181], v[44:47]
	ds_read_b128 v[240:243], v145 offset:53248
	v_mfma_f32_16x16x32_bf16 v[76:79], v[162:165], v[186:189], v[76:79]
	v_mfma_f32_16x16x32_bf16 v[68:71], v[170:173], v[186:189], v[68:71]
	v_mfma_f32_16x16x32_bf16 v[130:133], v[162:165], v[194:197], v[130:133]
	v_mfma_f32_16x16x32_bf16 v[92:95], v[170:173], v[194:197], v[92:95]
	ds_read_b128 v[244:247], v145 offset:54272
	v_mfma_f32_16x16x32_bf16 v[72:75], v[162:165], v[206:209], v[72:75]
	v_mfma_f32_16x16x32_bf16 v[64:67], v[170:173], v[206:209], v[64:67]
	v_mfma_f32_16x16x32_bf16 v[48:51], v[166:169], v[182:185], v[48:51]
	v_mfma_f32_16x16x32_bf16 v[44:47], v[174:177], v[182:185], v[44:47]
	ds_read_b128 v[248:251], v145 offset:55296
	v_mfma_f32_16x16x32_bf16 v[76:79], v[166:169], v[190:193], v[76:79]
	v_mfma_f32_16x16x32_bf16 v[68:71], v[174:177], v[190:193], v[68:71]
	v_mfma_f32_16x16x32_bf16 v[130:133], v[166:169], v[200:203], v[130:133]
	v_mfma_f32_16x16x32_bf16 v[92:95], v[174:177], v[200:203], v[92:95]
	v_mfma_f32_16x16x32_bf16 v[72:75], v[166:169], v[210:213], v[72:75]
	v_mfma_f32_16x16x32_bf16 v[64:67], v[174:177], v[210:213], v[64:67]
	s_setprio 0
	s_barrier
	s_add_i32 s30, s30, s22
	s_add_u32 s4, s72, 0x80
	s_addc_u32 s5, s73, 0
	s_mov_b32 m0, s30
	ds_read_b128 v[210:213], v145 offset:56320
	global_load_lds_dwordx4 v108, s[4:5]
	s_add_i32 m0, s30, 0x2000
	s_add_u32 s72, s72, 0x160080
	s_addc_u32 s73, s73, 0
	s_add_i32 s30, s31, s22
	global_load_lds_dwordx4 v134, s[4:5]
	s_mov_b32 m0, s30
	s_nop 0
	global_load_lds_dwordx4 v108, s[72:73]
	s_add_i32 m0, s30, 0x2000
	s_nop 0
	global_load_lds_dwordx4 v134, s[72:73]
	s_add_u32 s4, s80, 0xffea0080
	s_addc_u32 s5, s81, -1
	s_mov_b32 m0, s91
	s_nop 0
	global_load_lds_dwordx4 v108, s[4:5]
	s_mov_b32 m0, s86
	s_nop 0
	global_load_lds_dwordx4 v134, s[4:5]
	s_waitcnt vmcnt(6)
	s_waitcnt lgkmcnt(0)
	s_barrier
	s_setprio 1
	s_waitcnt lgkmcnt(0)
	v_mfma_f32_16x16x32_bf16 v[126:129], v[146:149], v[224:227], v[126:129]
	v_mfma_f32_16x16x32_bf16 v[122:125], v[154:157], v[224:227], v[122:125]
	v_mfma_f32_16x16x32_bf16 v[60:63], v[146:149], v[232:235], v[60:63]
	v_mfma_f32_16x16x32_bf16 v[40:43], v[154:157], v[232:235], v[40:43]
	v_mfma_f32_16x16x32_bf16 v[28:31], v[146:149], v[240:243], v[28:31]
	v_mfma_f32_16x16x32_bf16 v[24:27], v[154:157], v[240:243], v[24:27]
	v_mfma_f32_16x16x32_bf16 v[12:15], v[146:149], v[248:251], v[12:15]
	v_mfma_f32_16x16x32_bf16 v[8:11], v[154:157], v[248:251], v[8:11]
	v_mfma_f32_16x16x32_bf16 v[126:129], v[150:153], v[228:231], v[126:129]
	v_mfma_f32_16x16x32_bf16 v[122:125], v[158:161], v[228:231], v[122:125]
	v_mfma_f32_16x16x32_bf16 v[60:63], v[150:153], v[236:239], v[60:63]
	v_mfma_f32_16x16x32_bf16 v[40:43], v[158:161], v[236:239], v[40:43]
	v_mfma_f32_16x16x32_bf16 v[28:31], v[150:153], v[244:247], v[28:31]
	v_mfma_f32_16x16x32_bf16 v[24:27], v[158:161], v[244:247], v[24:27]
	v_mfma_f32_16x16x32_bf16 v[12:15], v[150:153], v[210:213], v[12:15]
	v_mfma_f32_16x16x32_bf16 v[8:11], v[158:161], v[210:213], v[8:11]
	s_setprio 0
	s_setprio 1
	v_mfma_f32_16x16x32_bf16 v[118:121], v[162:165], v[224:227], v[118:121]
	v_mfma_f32_16x16x32_bf16 v[114:117], v[170:173], v[224:227], v[114:117]
	v_mfma_f32_16x16x32_bf16 v[36:39], v[162:165], v[232:235], v[36:39]
	v_mfma_f32_16x16x32_bf16 v[32:35], v[170:173], v[232:235], v[32:35]
	v_mfma_f32_16x16x32_bf16 v[20:23], v[162:165], v[240:243], v[20:23]
	v_mfma_f32_16x16x32_bf16 v[16:19], v[170:173], v[240:243], v[16:19]
	v_mfma_f32_16x16x32_bf16 v[4:7], v[162:165], v[248:251], v[4:7]
	v_mfma_f32_16x16x32_bf16 v[0:3], v[170:173], v[248:251], v[0:3]
	v_mfma_f32_16x16x32_bf16 v[118:121], v[166:169], v[228:231], v[118:121]
	v_mfma_f32_16x16x32_bf16 v[114:117], v[174:177], v[228:231], v[114:117]
	v_mfma_f32_16x16x32_bf16 v[36:39], v[166:169], v[236:239], v[36:39]
	v_mfma_f32_16x16x32_bf16 v[32:35], v[174:177], v[236:239], v[32:35]
	v_mfma_f32_16x16x32_bf16 v[20:23], v[166:169], v[244:247], v[20:23]
	v_mfma_f32_16x16x32_bf16 v[16:19], v[174:177], v[244:247], v[16:19]
	v_mfma_f32_16x16x32_bf16 v[4:7], v[166:169], v[210:213], v[4:7]
	v_mfma_f32_16x16x32_bf16 v[0:3], v[174:177], v[210:213], v[0:3]
	s_setprio 0
	s_barrier
	s_add_u32 s57, s57, 0x100
	s_addc_u32 s59, s59, 0
	s_cmp_ge_i32 vcc_lo, s53
	s_mov_b64 s[82:83], s[70:71]
	s_mov_b32 s72, vcc_lo
	s_cbranch_scc0 .LBB0_1523
	s_mov_b64 s[4:5], 0x80
